# GEMM K-loop heads aligned to 64 bytes (placement only)
# speedup vs baseline: 1.0250x; 1.0044x over previous
.LBB0_109:
	v_mov_b64_e32 v[0:1], 0x200
	s_ashr_i32 s5, s4, 31
	v_cmp_lt_i64_e32 vcc, s[6:7], v[0:1]
	s_lshl_b64 s[6:7], s[4:5], 21
	v_readlane_b32 s12, v253, 29
	v_readlane_b32 s13, v253, 30
	s_add_u32 s6, s12, s6
	s_addc_u32 s7, s13, s7
	s_and_b64 s[12:13], vcc, exec
	s_cselect_b32 s5, s7, s21
	s_cselect_b32 s50, s6, s20
	s_ashr_i32 s1, s0, 31
	s_lshl_b64 s[12:13], s[0:1], 21
	v_readlane_b32 s1, v252, 4
	s_add_u32 s58, s1, s12
	v_readlane_b32 s1, v252, 5
	s_addc_u32 s59, s1, s13
	s_and_b64 s[12:13], vcc, exec
	s_cselect_b32 s1, s59, s9
	s_cselect_b32 s12, s58, s8
	s_add_u32 s60, s20, 0x100080
	s_addc_u32 s61, s21, 0
	s_add_u32 s13, s8, 0x100
	v_mov_b32_e32 v0, 0
	s_addc_u32 s14, s9, 0
	s_mov_b32 s15, -2
	v_mov_b32_e32 v1, v0
	v_mov_b32_e32 v2, v0
	v_mov_b32_e32 v3, v0
	v_mov_b32_e32 v4, v0
	v_mov_b32_e32 v5, v0
	v_mov_b32_e32 v6, v0
	v_mov_b32_e32 v7, v0
	v_mov_b32_e32 v8, v0
	v_mov_b32_e32 v9, v0
	v_mov_b32_e32 v10, v0
	v_mov_b32_e32 v11, v0
	v_mov_b32_e32 v12, v0
	v_mov_b32_e32 v13, v0
	v_mov_b32_e32 v14, v0
	v_mov_b32_e32 v15, v0
	v_mov_b32_e32 v16, v0
	v_mov_b32_e32 v17, v0
	v_mov_b32_e32 v18, v0
	v_mov_b32_e32 v19, v0
	v_mov_b32_e32 v20, v0
	v_mov_b32_e32 v21, v0
	v_mov_b32_e32 v22, v0
	v_mov_b32_e32 v23, v0
	v_mov_b32_e32 v24, v0
	v_mov_b32_e32 v25, v0
	v_mov_b32_e32 v26, v0
	v_mov_b32_e32 v27, v0
	v_mov_b32_e32 v28, v0
	v_mov_b32_e32 v29, v0
	v_mov_b32_e32 v30, v0
	v_mov_b32_e32 v31, v0
	v_mov_b32_e32 v64, v0
	v_mov_b32_e32 v65, v0
	v_mov_b32_e32 v66, v0
	v_mov_b32_e32 v67, v0
	v_mov_b32_e32 v68, v0
	v_mov_b32_e32 v69, v0
	v_mov_b32_e32 v70, v0
	v_mov_b32_e32 v71, v0
	v_mov_b32_e32 v72, v0
	v_mov_b32_e32 v73, v0
	v_mov_b32_e32 v74, v0
	v_mov_b32_e32 v75, v0
	v_mov_b32_e32 v76, v0
	v_mov_b32_e32 v77, v0
	v_mov_b32_e32 v78, v0
	v_mov_b32_e32 v79, v0
	v_mov_b32_e32 v80, v0
	v_mov_b32_e32 v81, v0
	v_mov_b32_e32 v82, v0
	v_mov_b32_e32 v83, v0
	v_mov_b32_e32 v84, v0
	v_mov_b32_e32 v85, v0
	v_mov_b32_e32 v86, v0
	v_mov_b32_e32 v87, v0
	v_mov_b32_e32 v88, v0
	v_mov_b32_e32 v89, v0
	v_mov_b32_e32 v90, v0
	v_mov_b32_e32 v91, v0
	v_mov_b32_e32 v92, v0
	v_mov_b32_e32 v93, v0
	v_mov_b32_e32 v94, v0
	v_mov_b32_e32 v95, v0
	v_mov_b32_e32 v32, v0
	v_mov_b32_e32 v33, v0
	v_mov_b32_e32 v34, v0
	v_mov_b32_e32 v35, v0
	v_mov_b32_e32 v36, v0
	v_mov_b32_e32 v37, v0
	v_mov_b32_e32 v38, v0
	v_mov_b32_e32 v39, v0
	v_mov_b32_e32 v40, v0
	v_mov_b32_e32 v41, v0
	v_mov_b32_e32 v42, v0
	v_mov_b32_e32 v43, v0
	v_mov_b32_e32 v44, v0
	v_mov_b32_e32 v45, v0
	v_mov_b32_e32 v46, v0
	v_mov_b32_e32 v47, v0
	v_mov_b32_e32 v48, v0
	v_mov_b32_e32 v49, v0
	v_mov_b32_e32 v50, v0
	v_mov_b32_e32 v51, v0
	v_mov_b32_e32 v52, v0
	v_mov_b32_e32 v53, v0
	v_mov_b32_e32 v54, v0
	v_mov_b32_e32 v55, v0
	v_mov_b32_e32 v56, v0
	v_mov_b32_e32 v57, v0
	v_mov_b32_e32 v58, v0
	v_mov_b32_e32 v59, v0
	v_mov_b32_e32 v60, v0
	v_mov_b32_e32 v61, v0
	v_mov_b32_e32 v62, v0
	v_mov_b32_e32 v63, v0
	v_mov_b32_e32 v96, v0
	v_mov_b32_e32 v97, v0
	v_mov_b32_e32 v98, v0
	v_mov_b32_e32 v99, v0
	v_mov_b32_e32 v100, v0
	v_mov_b32_e32 v101, v0
	v_mov_b32_e32 v102, v0
	v_mov_b32_e32 v103, v0
	v_mov_b32_e32 v104, v0
	v_mov_b32_e32 v105, v0
	v_mov_b32_e32 v106, v0
	v_mov_b32_e32 v107, v0
	v_mov_b32_e32 v108, v0
	v_mov_b32_e32 v109, v0
	v_mov_b32_e32 v110, v0
	v_mov_b32_e32 v111, v0
	v_mov_b32_e32 v112, v0
	v_mov_b32_e32 v113, v0
	v_mov_b32_e32 v114, v0
	v_mov_b32_e32 v115, v0
	v_mov_b32_e32 v116, v0
	v_mov_b32_e32 v117, v0
	v_mov_b32_e32 v118, v0
	v_mov_b32_e32 v119, v0
	v_mov_b32_e32 v120, v0
	v_mov_b32_e32 v121, v0
	v_mov_b32_e32 v122, v0
	v_mov_b32_e32 v123, v0
	v_mov_b32_e32 v124, v0
	v_mov_b32_e32 v125, v0
	v_mov_b32_e32 v126, v0
	v_mov_b32_e32 v127, v0
	.p2align 6

.LBB0_129:
	v_mov_b64_e32 v[0:1], 0x800
	s_ashr_i32 s5, s4, 31
	v_cmp_lt_i64_e32 vcc, s[6:7], v[0:1]
	s_lshl_b64 s[6:7], s[4:5], 19
	s_add_u32 s6, s28, s6
	s_addc_u32 s7, s29, s7
	s_and_b64 s[12:13], vcc, exec
	s_cselect_b32 s5, s7, s21
	s_cselect_b32 s10, s6, s20
	s_ashr_i32 s1, s0, 31
	s_lshl_b64 s[12:13], s[0:1], 19
	v_readlane_b32 s1, v252, 19
	s_add_u32 s58, s1, s12
	v_readlane_b32 s1, v252, 20
	s_addc_u32 s59, s1, s13
	s_and_b64 s[12:13], vcc, exec
	s_cselect_b32 s1, s59, s9
	s_cselect_b32 s12, s58, s8
	s_add_u32 s60, s20, 0x40080
	s_addc_u32 s61, s21, 0
	s_add_u32 s13, s8, 0x100
	v_mov_b32_e32 v0, 0
	s_addc_u32 s14, s9, 0
	s_mov_b32 s15, -2
	v_mov_b32_e32 v1, v0
	v_mov_b32_e32 v2, v0
	v_mov_b32_e32 v3, v0
	v_mov_b32_e32 v4, v0
	v_mov_b32_e32 v5, v0
	v_mov_b32_e32 v6, v0
	v_mov_b32_e32 v7, v0
	v_mov_b32_e32 v8, v0
	v_mov_b32_e32 v9, v0
	v_mov_b32_e32 v10, v0
	v_mov_b32_e32 v11, v0
	v_mov_b32_e32 v12, v0
	v_mov_b32_e32 v13, v0
	v_mov_b32_e32 v14, v0
	v_mov_b32_e32 v15, v0
	v_mov_b32_e32 v16, v0
	v_mov_b32_e32 v17, v0
	v_mov_b32_e32 v18, v0
	v_mov_b32_e32 v19, v0
	v_mov_b32_e32 v20, v0
	v_mov_b32_e32 v21, v0
	v_mov_b32_e32 v22, v0
	v_mov_b32_e32 v23, v0
	v_mov_b32_e32 v24, v0
	v_mov_b32_e32 v25, v0
	v_mov_b32_e32 v26, v0
	v_mov_b32_e32 v27, v0
	v_mov_b32_e32 v28, v0
	v_mov_b32_e32 v29, v0
	v_mov_b32_e32 v30, v0
	v_mov_b32_e32 v31, v0
	v_mov_b32_e32 v56, v0
	v_mov_b32_e32 v57, v0
	v_mov_b32_e32 v58, v0
	v_mov_b32_e32 v59, v0
	v_mov_b32_e32 v60, v0
	v_mov_b32_e32 v61, v0
	v_mov_b32_e32 v62, v0
	v_mov_b32_e32 v63, v0
	v_mov_b32_e32 v72, v0
	v_mov_b32_e32 v73, v0
	v_mov_b32_e32 v74, v0
	v_mov_b32_e32 v75, v0
	v_mov_b32_e32 v76, v0
	v_mov_b32_e32 v77, v0
	v_mov_b32_e32 v78, v0
	v_mov_b32_e32 v79, v0
	v_mov_b32_e32 v80, v0
	v_mov_b32_e32 v81, v0
	v_mov_b32_e32 v82, v0
	v_mov_b32_e32 v83, v0
	v_mov_b32_e32 v84, v0
	v_mov_b32_e32 v85, v0
	v_mov_b32_e32 v86, v0
	v_mov_b32_e32 v87, v0
	v_mov_b32_e32 v88, v0
	v_mov_b32_e32 v89, v0
	v_mov_b32_e32 v90, v0
	v_mov_b32_e32 v91, v0
	v_mov_b32_e32 v92, v0
	v_mov_b32_e32 v93, v0
	v_mov_b32_e32 v94, v0
	v_mov_b32_e32 v95, v0
	v_mov_b32_e32 v32, v0
	v_mov_b32_e32 v33, v0
	v_mov_b32_e32 v34, v0
	v_mov_b32_e32 v35, v0
	v_mov_b32_e32 v36, v0
	v_mov_b32_e32 v37, v0
	v_mov_b32_e32 v38, v0
	v_mov_b32_e32 v39, v0
	v_mov_b32_e32 v40, v0
	v_mov_b32_e32 v41, v0
	v_mov_b32_e32 v42, v0
	v_mov_b32_e32 v43, v0
	v_mov_b32_e32 v44, v0
	v_mov_b32_e32 v45, v0
	v_mov_b32_e32 v46, v0
	v_mov_b32_e32 v47, v0
	v_mov_b32_e32 v48, v0
	v_mov_b32_e32 v49, v0
	v_mov_b32_e32 v50, v0
	v_mov_b32_e32 v51, v0
	v_mov_b32_e32 v52, v0
	v_mov_b32_e32 v53, v0
	v_mov_b32_e32 v54, v0
	v_mov_b32_e32 v55, v0
	v_mov_b32_e32 v64, v0
	v_mov_b32_e32 v65, v0
	v_mov_b32_e32 v66, v0
	v_mov_b32_e32 v67, v0
	v_mov_b32_e32 v68, v0
	v_mov_b32_e32 v69, v0
	v_mov_b32_e32 v70, v0
	v_mov_b32_e32 v71, v0
	v_mov_b32_e32 v96, v0
	v_mov_b32_e32 v97, v0
	v_mov_b32_e32 v98, v0
	v_mov_b32_e32 v99, v0
	v_mov_b32_e32 v100, v0
	v_mov_b32_e32 v101, v0
	v_mov_b32_e32 v102, v0
	v_mov_b32_e32 v103, v0
	v_mov_b32_e32 v104, v0
	v_mov_b32_e32 v105, v0
	v_mov_b32_e32 v106, v0
	v_mov_b32_e32 v107, v0
	v_mov_b32_e32 v108, v0
	v_mov_b32_e32 v109, v0
	v_mov_b32_e32 v110, v0
	v_mov_b32_e32 v111, v0
	v_mov_b32_e32 v112, v0
	v_mov_b32_e32 v113, v0
	v_mov_b32_e32 v114, v0
	v_mov_b32_e32 v115, v0
	v_mov_b32_e32 v116, v0
	v_mov_b32_e32 v117, v0
	v_mov_b32_e32 v118, v0
	v_mov_b32_e32 v119, v0
	v_mov_b32_e32 v120, v0
	v_mov_b32_e32 v121, v0
	v_mov_b32_e32 v122, v0
	v_mov_b32_e32 v123, v0
	v_mov_b32_e32 v124, v0
	v_mov_b32_e32 v125, v0
	v_mov_b32_e32 v126, v0
	v_mov_b32_e32 v127, v0
	.p2align 6

.LBB0_154:
	s_ashr_i32 s59, s58, 31
	s_lshl_b64 s[12:13], s[58:59], 19
	v_readlane_b32 s14, v253, 8
	v_mov_b64_e32 v[0:1], 0x200
	v_readlane_b32 s15, v253, 9
	s_add_u32 s64, s14, s12
	v_cmp_lt_i64_e32 vcc, s[20:21], v[0:1]
	s_addc_u32 s65, s15, s13
	s_and_b64 s[12:13], vcc, exec
	s_cselect_b32 s20, s65, s1
	s_cselect_b32 s21, s64, s0
	s_ashr_i32 s7, s6, 31
	s_lshl_b64 s[12:13], s[6:7], 19
	v_readlane_b32 s7, v253, 10
	s_add_u32 s66, s7, s12
	v_readlane_b32 s7, v253, 11
	s_addc_u32 s67, s7, s13
	s_and_b64 s[12:13], vcc, exec
	s_cselect_b32 s7, s67, s9
	s_cselect_b32 s12, s66, s8
	s_add_u32 s0, s0, 0x40080
	s_addc_u32 s1, s1, 0
	s_add_u32 s13, s8, 0x100
	v_mov_b32_e32 v0, 0
	s_addc_u32 s14, s9, 0
	s_mov_b32 s15, -2
	v_mov_b32_e32 v1, v0
	v_mov_b32_e32 v2, v0
	v_mov_b32_e32 v3, v0
	v_mov_b32_e32 v4, v0
	v_mov_b32_e32 v5, v0
	v_mov_b32_e32 v6, v0
	v_mov_b32_e32 v7, v0
	v_mov_b32_e32 v8, v0
	v_mov_b32_e32 v9, v0
	v_mov_b32_e32 v10, v0
	v_mov_b32_e32 v11, v0
	v_mov_b32_e32 v12, v0
	v_mov_b32_e32 v13, v0
	v_mov_b32_e32 v14, v0
	v_mov_b32_e32 v15, v0
	v_mov_b32_e32 v16, v0
	v_mov_b32_e32 v17, v0
	v_mov_b32_e32 v18, v0
	v_mov_b32_e32 v19, v0
	v_mov_b32_e32 v20, v0
	v_mov_b32_e32 v21, v0
	v_mov_b32_e32 v22, v0
	v_mov_b32_e32 v23, v0
	v_mov_b32_e32 v24, v0
	v_mov_b32_e32 v25, v0
	v_mov_b32_e32 v26, v0
	v_mov_b32_e32 v27, v0
	v_mov_b32_e32 v28, v0
	v_mov_b32_e32 v29, v0
	v_mov_b32_e32 v30, v0
	v_mov_b32_e32 v31, v0
	v_mov_b32_e32 v64, v0
	v_mov_b32_e32 v65, v0
	v_mov_b32_e32 v66, v0
	v_mov_b32_e32 v67, v0
	v_mov_b32_e32 v68, v0
	v_mov_b32_e32 v69, v0
	v_mov_b32_e32 v70, v0
	v_mov_b32_e32 v71, v0
	v_mov_b32_e32 v72, v0
	v_mov_b32_e32 v73, v0
	v_mov_b32_e32 v74, v0
	v_mov_b32_e32 v75, v0
	v_mov_b32_e32 v76, v0
	v_mov_b32_e32 v77, v0
	v_mov_b32_e32 v78, v0
	v_mov_b32_e32 v79, v0
	v_mov_b32_e32 v80, v0
	v_mov_b32_e32 v81, v0
	v_mov_b32_e32 v82, v0
	v_mov_b32_e32 v83, v0
	v_mov_b32_e32 v84, v0
	v_mov_b32_e32 v85, v0
	v_mov_b32_e32 v86, v0
	v_mov_b32_e32 v87, v0
	v_mov_b32_e32 v88, v0
	v_mov_b32_e32 v89, v0
	v_mov_b32_e32 v90, v0
	v_mov_b32_e32 v91, v0
	v_mov_b32_e32 v92, v0
	v_mov_b32_e32 v93, v0
	v_mov_b32_e32 v94, v0
	v_mov_b32_e32 v95, v0
	v_mov_b32_e32 v32, v0
	v_mov_b32_e32 v33, v0
	v_mov_b32_e32 v34, v0
	v_mov_b32_e32 v35, v0
	v_mov_b32_e32 v36, v0
	v_mov_b32_e32 v37, v0
	v_mov_b32_e32 v38, v0
	v_mov_b32_e32 v39, v0
	v_mov_b32_e32 v40, v0
	v_mov_b32_e32 v41, v0
	v_mov_b32_e32 v42, v0
	v_mov_b32_e32 v43, v0
	v_mov_b32_e32 v44, v0
	v_mov_b32_e32 v45, v0
	v_mov_b32_e32 v46, v0
	v_mov_b32_e32 v47, v0
	v_mov_b32_e32 v48, v0
	v_mov_b32_e32 v49, v0
	v_mov_b32_e32 v50, v0
	v_mov_b32_e32 v51, v0
	v_mov_b32_e32 v52, v0
	v_mov_b32_e32 v53, v0
	v_mov_b32_e32 v54, v0
	v_mov_b32_e32 v55, v0
	v_mov_b32_e32 v56, v0
	v_mov_b32_e32 v57, v0
	v_mov_b32_e32 v58, v0
	v_mov_b32_e32 v59, v0
	v_mov_b32_e32 v60, v0
	v_mov_b32_e32 v61, v0
	v_mov_b32_e32 v62, v0
	v_mov_b32_e32 v63, v0
	v_mov_b32_e32 v96, v0
	v_mov_b32_e32 v97, v0
	v_mov_b32_e32 v98, v0
	v_mov_b32_e32 v99, v0
	v_mov_b32_e32 v100, v0
	v_mov_b32_e32 v101, v0
	v_mov_b32_e32 v102, v0
	v_mov_b32_e32 v103, v0
	v_mov_b32_e32 v104, v0
	v_mov_b32_e32 v105, v0
	v_mov_b32_e32 v106, v0
	v_mov_b32_e32 v107, v0
	v_mov_b32_e32 v108, v0
	v_mov_b32_e32 v109, v0
	v_mov_b32_e32 v110, v0
	v_mov_b32_e32 v111, v0
	v_mov_b32_e32 v112, v0
	v_mov_b32_e32 v113, v0
	v_mov_b32_e32 v114, v0
	v_mov_b32_e32 v115, v0
	v_mov_b32_e32 v116, v0
	v_mov_b32_e32 v117, v0
	v_mov_b32_e32 v118, v0
	v_mov_b32_e32 v119, v0
	v_mov_b32_e32 v120, v0
	v_mov_b32_e32 v121, v0
	v_mov_b32_e32 v122, v0
	v_mov_b32_e32 v123, v0
	v_mov_b32_e32 v124, v0
	v_mov_b32_e32 v125, v0
	v_mov_b32_e32 v126, v0
	v_mov_b32_e32 v127, v0
	.p2align 6

.LBB0_250:
	v_mov_b64_e32 v[0:1], 0x200
	s_ashr_i32 s5, s4, 31
	v_cmp_lt_i64_e32 vcc, s[6:7], v[0:1]
	s_lshl_b64 s[6:7], s[4:5], 17
	s_add_u32 s6, s16, s6
	s_addc_u32 s7, s17, s7
	s_and_b64 s[8:9], vcc, exec
	s_cselect_b32 s5, s7, s65
	s_cselect_b32 s50, s6, s64
	s_ashr_i32 s1, s0, 31
	s_lshl_b64 s[8:9], s[0:1], 17
	v_readlane_b32 s12, v252, 36
	v_readlane_b32 s13, v252, 37
	s_add_u32 s58, s12, s8
	s_addc_u32 s59, s13, s9
	s_and_b64 s[8:9], vcc, exec
	v_mov_b32_e32 v0, 0
	s_cselect_b32 s1, s59, s61
	s_cselect_b32 s12, s58, s60
	s_mov_b32 s8, 0
	s_mov_b64 s[66:67], -1
	s_mov_b64 s[62:63], 0
	v_mov_b32_e32 v1, v0
	v_mov_b32_e32 v2, v0
	v_mov_b32_e32 v3, v0
	v_mov_b32_e32 v4, v0
	v_mov_b32_e32 v5, v0
	v_mov_b32_e32 v6, v0
	v_mov_b32_e32 v7, v0
	v_mov_b32_e32 v8, v0
	v_mov_b32_e32 v9, v0
	v_mov_b32_e32 v10, v0
	v_mov_b32_e32 v11, v0
	v_mov_b32_e32 v12, v0
	v_mov_b32_e32 v13, v0
	v_mov_b32_e32 v14, v0
	v_mov_b32_e32 v15, v0
	v_mov_b32_e32 v16, v0
	v_mov_b32_e32 v17, v0
	v_mov_b32_e32 v18, v0
	v_mov_b32_e32 v19, v0
	v_mov_b32_e32 v20, v0
	v_mov_b32_e32 v21, v0
	v_mov_b32_e32 v22, v0
	v_mov_b32_e32 v23, v0
	v_mov_b32_e32 v24, v0
	v_mov_b32_e32 v25, v0
	v_mov_b32_e32 v26, v0
	v_mov_b32_e32 v27, v0
	v_mov_b32_e32 v28, v0
	v_mov_b32_e32 v29, v0
	v_mov_b32_e32 v30, v0
	v_mov_b32_e32 v31, v0
	v_mov_b32_e32 v56, v0
	v_mov_b32_e32 v57, v0
	v_mov_b32_e32 v58, v0
	v_mov_b32_e32 v59, v0
	v_mov_b32_e32 v60, v0
	v_mov_b32_e32 v61, v0
	v_mov_b32_e32 v62, v0
	v_mov_b32_e32 v63, v0
	v_mov_b32_e32 v72, v0
	v_mov_b32_e32 v73, v0
	v_mov_b32_e32 v74, v0
	v_mov_b32_e32 v75, v0
	v_mov_b32_e32 v76, v0
	v_mov_b32_e32 v77, v0
	v_mov_b32_e32 v78, v0
	v_mov_b32_e32 v79, v0
	v_mov_b32_e32 v80, v0
	v_mov_b32_e32 v81, v0
	v_mov_b32_e32 v82, v0
	v_mov_b32_e32 v83, v0
	v_mov_b32_e32 v84, v0
	v_mov_b32_e32 v85, v0
	v_mov_b32_e32 v86, v0
	v_mov_b32_e32 v87, v0
	v_mov_b32_e32 v88, v0
	v_mov_b32_e32 v89, v0
	v_mov_b32_e32 v90, v0
	v_mov_b32_e32 v91, v0
	v_mov_b32_e32 v92, v0
	v_mov_b32_e32 v93, v0
	v_mov_b32_e32 v94, v0
	v_mov_b32_e32 v95, v0
	v_mov_b32_e32 v32, v0
	v_mov_b32_e32 v33, v0
	v_mov_b32_e32 v34, v0
	v_mov_b32_e32 v35, v0
	v_mov_b32_e32 v36, v0
	v_mov_b32_e32 v37, v0
	v_mov_b32_e32 v38, v0
	v_mov_b32_e32 v39, v0
	v_mov_b32_e32 v40, v0
	v_mov_b32_e32 v41, v0
	v_mov_b32_e32 v42, v0
	v_mov_b32_e32 v43, v0
	v_mov_b32_e32 v44, v0
	v_mov_b32_e32 v45, v0
	v_mov_b32_e32 v46, v0
	v_mov_b32_e32 v47, v0
	v_mov_b32_e32 v48, v0
	v_mov_b32_e32 v49, v0
	v_mov_b32_e32 v50, v0
	v_mov_b32_e32 v51, v0
	v_mov_b32_e32 v52, v0
	v_mov_b32_e32 v53, v0
	v_mov_b32_e32 v54, v0
	v_mov_b32_e32 v55, v0
	v_mov_b32_e32 v64, v0
	v_mov_b32_e32 v65, v0
	v_mov_b32_e32 v66, v0
	v_mov_b32_e32 v67, v0
	v_mov_b32_e32 v68, v0
	v_mov_b32_e32 v69, v0
	v_mov_b32_e32 v70, v0
	v_mov_b32_e32 v71, v0
	v_mov_b32_e32 v96, v0
	v_mov_b32_e32 v97, v0
	v_mov_b32_e32 v98, v0
	v_mov_b32_e32 v99, v0
	v_mov_b32_e32 v100, v0
	v_mov_b32_e32 v101, v0
	v_mov_b32_e32 v102, v0
	v_mov_b32_e32 v103, v0
	v_mov_b32_e32 v104, v0
	v_mov_b32_e32 v105, v0
	v_mov_b32_e32 v106, v0
	v_mov_b32_e32 v107, v0
	v_mov_b32_e32 v108, v0
	v_mov_b32_e32 v109, v0
	v_mov_b32_e32 v110, v0
	v_mov_b32_e32 v111, v0
	v_mov_b32_e32 v112, v0
	v_mov_b32_e32 v113, v0
	v_mov_b32_e32 v114, v0
	v_mov_b32_e32 v115, v0
	v_mov_b32_e32 v116, v0
	v_mov_b32_e32 v117, v0
	v_mov_b32_e32 v118, v0
	v_mov_b32_e32 v119, v0
	v_mov_b32_e32 v120, v0
	v_mov_b32_e32 v121, v0
	v_mov_b32_e32 v122, v0
	v_mov_b32_e32 v123, v0
	v_mov_b32_e32 v124, v0
	v_mov_b32_e32 v125, v0
	v_mov_b32_e32 v126, v0
	v_mov_b32_e32 v127, v0
	.p2align 6

.LBB0_283:
	s_ashr_i32 s7, s6, 31
	s_lshl_b64 s[12:13], s[6:7], 19
	v_mov_b64_e32 v[0:1], 0x600
	s_add_u32 s58, s28, s12
	v_cmp_lt_i64_e32 vcc, s[20:21], v[0:1]
	s_addc_u32 s59, s29, s13
	s_and_b64 s[12:13], vcc, exec
	s_cselect_b32 s7, s59, s1
	s_cselect_b32 s20, s58, s0
	s_ashr_i32 s5, s4, 31
	s_lshl_b64 s[12:13], s[4:5], 19
	v_readlane_b32 s5, v252, 51
	s_add_u32 s64, s5, s12
	v_readlane_b32 s5, v252, 52
	s_addc_u32 s65, s5, s13
	s_and_b64 s[12:13], vcc, exec
	s_cselect_b32 s5, s65, s9
	s_cselect_b32 s12, s64, s8
	s_add_u32 s0, s0, 0x40080
	s_addc_u32 s1, s1, 0
	s_add_u32 s13, s8, 0x100
	v_mov_b32_e32 v0, 0
	s_addc_u32 s14, s9, 0
	s_mov_b32 s15, -2
	v_mov_b32_e32 v1, v0
	v_mov_b32_e32 v2, v0
	v_mov_b32_e32 v3, v0
	v_mov_b32_e32 v4, v0
	v_mov_b32_e32 v5, v0
	v_mov_b32_e32 v6, v0
	v_mov_b32_e32 v7, v0
	v_mov_b32_e32 v8, v0
	v_mov_b32_e32 v9, v0
	v_mov_b32_e32 v10, v0
	v_mov_b32_e32 v11, v0
	v_mov_b32_e32 v12, v0
	v_mov_b32_e32 v13, v0
	v_mov_b32_e32 v14, v0
	v_mov_b32_e32 v15, v0
	v_mov_b32_e32 v16, v0
	v_mov_b32_e32 v17, v0
	v_mov_b32_e32 v18, v0
	v_mov_b32_e32 v19, v0
	v_mov_b32_e32 v20, v0
	v_mov_b32_e32 v21, v0
	v_mov_b32_e32 v22, v0
	v_mov_b32_e32 v23, v0
	v_mov_b32_e32 v24, v0
	v_mov_b32_e32 v25, v0
	v_mov_b32_e32 v26, v0
	v_mov_b32_e32 v27, v0
	v_mov_b32_e32 v28, v0
	v_mov_b32_e32 v29, v0
	v_mov_b32_e32 v30, v0
	v_mov_b32_e32 v31, v0
	v_mov_b32_e32 v52, v0
	v_mov_b32_e32 v53, v0
	v_mov_b32_e32 v54, v0
	v_mov_b32_e32 v55, v0
	v_mov_b32_e32 v60, v0
	v_mov_b32_e32 v61, v0
	v_mov_b32_e32 v62, v0
	v_mov_b32_e32 v63, v0
	v_mov_b32_e32 v72, v0
	v_mov_b32_e32 v73, v0
	v_mov_b32_e32 v74, v0
	v_mov_b32_e32 v75, v0
	v_mov_b32_e32 v76, v0
	v_mov_b32_e32 v77, v0
	v_mov_b32_e32 v78, v0
	v_mov_b32_e32 v79, v0
	v_mov_b32_e32 v80, v0
	v_mov_b32_e32 v81, v0
	v_mov_b32_e32 v82, v0
	v_mov_b32_e32 v83, v0
	v_mov_b32_e32 v84, v0
	v_mov_b32_e32 v85, v0
	v_mov_b32_e32 v86, v0
	v_mov_b32_e32 v87, v0
	v_mov_b32_e32 v88, v0
	v_mov_b32_e32 v89, v0
	v_mov_b32_e32 v90, v0
	v_mov_b32_e32 v91, v0
	v_mov_b32_e32 v92, v0
	v_mov_b32_e32 v93, v0
	v_mov_b32_e32 v94, v0
	v_mov_b32_e32 v95, v0
	v_mov_b32_e32 v32, v0
	v_mov_b32_e32 v33, v0
	v_mov_b32_e32 v34, v0
	v_mov_b32_e32 v35, v0
	v_mov_b32_e32 v36, v0
	v_mov_b32_e32 v37, v0
	v_mov_b32_e32 v38, v0
	v_mov_b32_e32 v39, v0
	v_mov_b32_e32 v40, v0
	v_mov_b32_e32 v41, v0
	v_mov_b32_e32 v42, v0
	v_mov_b32_e32 v43, v0
	v_mov_b32_e32 v44, v0
	v_mov_b32_e32 v45, v0
	v_mov_b32_e32 v46, v0
	v_mov_b32_e32 v47, v0
	v_mov_b32_e32 v48, v0
	v_mov_b32_e32 v49, v0
	v_mov_b32_e32 v50, v0
	v_mov_b32_e32 v51, v0
	v_mov_b32_e32 v56, v0
	v_mov_b32_e32 v57, v0
	v_mov_b32_e32 v58, v0
	v_mov_b32_e32 v59, v0
	v_mov_b32_e32 v64, v0
	v_mov_b32_e32 v65, v0
	v_mov_b32_e32 v66, v0
	v_mov_b32_e32 v67, v0
	v_mov_b32_e32 v68, v0
	v_mov_b32_e32 v69, v0
	v_mov_b32_e32 v70, v0
	v_mov_b32_e32 v71, v0
	v_mov_b32_e32 v96, v0
	v_mov_b32_e32 v97, v0
	v_mov_b32_e32 v98, v0
	v_mov_b32_e32 v99, v0
	v_mov_b32_e32 v100, v0
	v_mov_b32_e32 v101, v0
	v_mov_b32_e32 v102, v0
	v_mov_b32_e32 v103, v0
	v_mov_b32_e32 v104, v0
	v_mov_b32_e32 v105, v0
	v_mov_b32_e32 v106, v0
	v_mov_b32_e32 v107, v0
	v_mov_b32_e32 v108, v0
	v_mov_b32_e32 v109, v0
	v_mov_b32_e32 v110, v0
	v_mov_b32_e32 v111, v0
	v_mov_b32_e32 v112, v0
	v_mov_b32_e32 v113, v0
	v_mov_b32_e32 v114, v0
	v_mov_b32_e32 v115, v0
	v_mov_b32_e32 v116, v0
	v_mov_b32_e32 v117, v0
	v_mov_b32_e32 v118, v0
	v_mov_b32_e32 v119, v0
	v_mov_b32_e32 v120, v0
	v_mov_b32_e32 v121, v0
	v_mov_b32_e32 v122, v0
	v_mov_b32_e32 v123, v0
	v_mov_b32_e32 v124, v0
	v_mov_b32_e32 v125, v0
	v_mov_b32_e32 v126, v0
	v_mov_b32_e32 v127, v0
	.p2align 6

.LBB0_316:
	s_ashr_i32 s7, s6, 31
	s_lshl_b64 s[12:13], s[6:7], 21
	v_readlane_b32 s14, v253, 29
	v_mov_b64_e32 v[0:1], 0x200
	v_readlane_b32 s15, v253, 30
	s_add_u32 s58, s14, s12
	v_cmp_lt_i64_e32 vcc, s[36:37], v[0:1]
	s_addc_u32 s59, s15, s13
	s_and_b64 s[12:13], vcc, exec
	s_cselect_b32 s7, s59, s21
	s_cselect_b32 s36, s58, s20
	s_ashr_i32 s1, s0, 31
	s_lshl_b64 s[12:13], s[0:1], 21
	s_add_u32 s64, s83, s12
	v_readlane_b32 s1, v253, 22
	s_addc_u32 s65, s1, s13
	s_and_b64 s[12:13], vcc, exec
	s_cselect_b32 s1, s65, s9
	s_cselect_b32 s12, s64, s8
	s_add_u32 s60, s20, 0x100080
	s_addc_u32 s61, s21, 0
	s_add_u32 s13, s8, 0x100
	v_mov_b32_e32 v0, 0
	s_addc_u32 s14, s9, 0
	s_mov_b32 s15, -2
	v_mov_b32_e32 v1, v0
	v_mov_b32_e32 v2, v0
	v_mov_b32_e32 v3, v0
	v_mov_b32_e32 v4, v0
	v_mov_b32_e32 v5, v0
	v_mov_b32_e32 v6, v0
	v_mov_b32_e32 v7, v0
	v_mov_b32_e32 v8, v0
	v_mov_b32_e32 v9, v0
	v_mov_b32_e32 v10, v0
	v_mov_b32_e32 v11, v0
	v_mov_b32_e32 v12, v0
	v_mov_b32_e32 v13, v0
	v_mov_b32_e32 v14, v0
	v_mov_b32_e32 v15, v0
	v_mov_b32_e32 v16, v0
	v_mov_b32_e32 v17, v0
	v_mov_b32_e32 v18, v0
	v_mov_b32_e32 v19, v0
	v_mov_b32_e32 v20, v0
	v_mov_b32_e32 v21, v0
	v_mov_b32_e32 v22, v0
	v_mov_b32_e32 v23, v0
	v_mov_b32_e32 v24, v0
	v_mov_b32_e32 v25, v0
	v_mov_b32_e32 v26, v0
	v_mov_b32_e32 v27, v0
	v_mov_b32_e32 v28, v0
	v_mov_b32_e32 v29, v0
	v_mov_b32_e32 v30, v0
	v_mov_b32_e32 v31, v0
	v_mov_b32_e32 v64, v0
	v_mov_b32_e32 v65, v0
	v_mov_b32_e32 v66, v0
	v_mov_b32_e32 v67, v0
	v_mov_b32_e32 v68, v0
	v_mov_b32_e32 v69, v0
	v_mov_b32_e32 v70, v0
	v_mov_b32_e32 v71, v0
	v_mov_b32_e32 v72, v0
	v_mov_b32_e32 v73, v0
	v_mov_b32_e32 v74, v0
	v_mov_b32_e32 v75, v0
	v_mov_b32_e32 v76, v0
	v_mov_b32_e32 v77, v0
	v_mov_b32_e32 v78, v0
	v_mov_b32_e32 v79, v0
	v_mov_b32_e32 v80, v0
	v_mov_b32_e32 v81, v0
	v_mov_b32_e32 v82, v0
	v_mov_b32_e32 v83, v0
	v_mov_b32_e32 v84, v0
	v_mov_b32_e32 v85, v0
	v_mov_b32_e32 v86, v0
	v_mov_b32_e32 v87, v0
	v_mov_b32_e32 v88, v0
	v_mov_b32_e32 v89, v0
	v_mov_b32_e32 v90, v0
	v_mov_b32_e32 v91, v0
	v_mov_b32_e32 v92, v0
	v_mov_b32_e32 v93, v0
	v_mov_b32_e32 v94, v0
	v_mov_b32_e32 v95, v0
	v_mov_b32_e32 v32, v0
	v_mov_b32_e32 v33, v0
	v_mov_b32_e32 v34, v0
	v_mov_b32_e32 v35, v0
	v_mov_b32_e32 v36, v0
	v_mov_b32_e32 v37, v0
	v_mov_b32_e32 v38, v0
	v_mov_b32_e32 v39, v0
	v_mov_b32_e32 v40, v0
	v_mov_b32_e32 v41, v0
	v_mov_b32_e32 v42, v0
	v_mov_b32_e32 v43, v0
	v_mov_b32_e32 v44, v0
	v_mov_b32_e32 v45, v0
	v_mov_b32_e32 v46, v0
	v_mov_b32_e32 v47, v0
	v_mov_b32_e32 v48, v0
	v_mov_b32_e32 v49, v0
	v_mov_b32_e32 v50, v0
	v_mov_b32_e32 v51, v0
	v_mov_b32_e32 v52, v0
	v_mov_b32_e32 v53, v0
	v_mov_b32_e32 v54, v0
	v_mov_b32_e32 v55, v0
	v_mov_b32_e32 v56, v0
	v_mov_b32_e32 v57, v0
	v_mov_b32_e32 v58, v0
	v_mov_b32_e32 v59, v0
	v_mov_b32_e32 v60, v0
	v_mov_b32_e32 v61, v0
	v_mov_b32_e32 v62, v0
	v_mov_b32_e32 v63, v0
	v_mov_b32_e32 v96, v0
	v_mov_b32_e32 v97, v0
	v_mov_b32_e32 v98, v0
	v_mov_b32_e32 v99, v0
	v_mov_b32_e32 v100, v0
	v_mov_b32_e32 v101, v0
	v_mov_b32_e32 v102, v0
	v_mov_b32_e32 v103, v0
	v_mov_b32_e32 v104, v0
	v_mov_b32_e32 v105, v0
	v_mov_b32_e32 v106, v0
	v_mov_b32_e32 v107, v0
	v_mov_b32_e32 v108, v0
	v_mov_b32_e32 v109, v0
	v_mov_b32_e32 v110, v0
	v_mov_b32_e32 v111, v0
	v_mov_b32_e32 v112, v0
	v_mov_b32_e32 v113, v0
	v_mov_b32_e32 v114, v0
	v_mov_b32_e32 v115, v0
	v_mov_b32_e32 v116, v0
	v_mov_b32_e32 v117, v0
	v_mov_b32_e32 v118, v0
	v_mov_b32_e32 v119, v0
	v_mov_b32_e32 v128, v0
	v_mov_b32_e32 v129, v0
	v_mov_b32_e32 v130, v0
	v_mov_b32_e32 v131, v0
	v_mov_b32_e32 v132, v0
	v_mov_b32_e32 v133, v0
	v_mov_b32_e32 v134, v0
	v_mov_b32_e32 v135, v0
	.p2align 6

.LBB0_349:
	v_mov_b64_e32 v[0:1], 0x800
	s_ashr_i32 s5, s4, 31
	v_cmp_lt_i64_e32 vcc, s[6:7], v[0:1]
	s_lshl_b64 s[6:7], s[4:5], 19
	s_add_u32 s6, s28, s6
	s_addc_u32 s7, s29, s7
	s_and_b64 s[12:13], vcc, exec
	s_cselect_b32 s5, s7, s21
	s_cselect_b32 s10, s6, s20
	s_ashr_i32 s1, s0, 31
	s_lshl_b64 s[12:13], s[0:1], 19
	s_add_u32 s58, s87, s12
	v_readlane_b32 s1, v252, 63
	s_addc_u32 s59, s1, s13
	s_and_b64 s[12:13], vcc, exec
	s_cselect_b32 s1, s59, s9
	s_cselect_b32 s12, s58, s8
	s_add_u32 s60, s20, 0x40080
	s_addc_u32 s61, s21, 0
	s_add_u32 s13, s8, 0x100
	v_mov_b32_e32 v0, 0
	s_addc_u32 s14, s9, 0
	s_mov_b32 s15, -2
	v_mov_b32_e32 v1, v0
	v_mov_b32_e32 v2, v0
	v_mov_b32_e32 v3, v0
	v_mov_b32_e32 v4, v0
	v_mov_b32_e32 v5, v0
	v_mov_b32_e32 v6, v0
	v_mov_b32_e32 v7, v0
	v_mov_b32_e32 v8, v0
	v_mov_b32_e32 v9, v0
	v_mov_b32_e32 v10, v0
	v_mov_b32_e32 v11, v0
	v_mov_b32_e32 v12, v0
	v_mov_b32_e32 v13, v0
	v_mov_b32_e32 v14, v0
	v_mov_b32_e32 v15, v0
	v_mov_b32_e32 v16, v0
	v_mov_b32_e32 v17, v0
	v_mov_b32_e32 v18, v0
	v_mov_b32_e32 v19, v0
	v_mov_b32_e32 v20, v0
	v_mov_b32_e32 v21, v0
	v_mov_b32_e32 v22, v0
	v_mov_b32_e32 v23, v0
	v_mov_b32_e32 v24, v0
	v_mov_b32_e32 v25, v0
	v_mov_b32_e32 v26, v0
	v_mov_b32_e32 v27, v0
	v_mov_b32_e32 v28, v0
	v_mov_b32_e32 v29, v0
	v_mov_b32_e32 v30, v0
	v_mov_b32_e32 v31, v0
	v_mov_b32_e32 v56, v0
	v_mov_b32_e32 v57, v0
	v_mov_b32_e32 v58, v0
	v_mov_b32_e32 v59, v0
	v_mov_b32_e32 v60, v0
	v_mov_b32_e32 v61, v0
	v_mov_b32_e32 v62, v0
	v_mov_b32_e32 v63, v0
	v_mov_b32_e32 v72, v0
	v_mov_b32_e32 v73, v0
	v_mov_b32_e32 v74, v0
	v_mov_b32_e32 v75, v0
	v_mov_b32_e32 v76, v0
	v_mov_b32_e32 v77, v0
	v_mov_b32_e32 v78, v0
	v_mov_b32_e32 v79, v0
	v_mov_b32_e32 v80, v0
	v_mov_b32_e32 v81, v0
	v_mov_b32_e32 v82, v0
	v_mov_b32_e32 v83, v0
	v_mov_b32_e32 v84, v0
	v_mov_b32_e32 v85, v0
	v_mov_b32_e32 v86, v0
	v_mov_b32_e32 v87, v0
	v_mov_b32_e32 v88, v0
	v_mov_b32_e32 v89, v0
	v_mov_b32_e32 v90, v0
	v_mov_b32_e32 v91, v0
	v_mov_b32_e32 v92, v0
	v_mov_b32_e32 v93, v0
	v_mov_b32_e32 v94, v0
	v_mov_b32_e32 v95, v0
	v_mov_b32_e32 v32, v0
	v_mov_b32_e32 v33, v0
	v_mov_b32_e32 v34, v0
	v_mov_b32_e32 v35, v0
	v_mov_b32_e32 v36, v0
	v_mov_b32_e32 v37, v0
	v_mov_b32_e32 v38, v0
	v_mov_b32_e32 v39, v0
	v_mov_b32_e32 v40, v0
	v_mov_b32_e32 v41, v0
	v_mov_b32_e32 v42, v0
	v_mov_b32_e32 v43, v0
	v_mov_b32_e32 v44, v0
	v_mov_b32_e32 v45, v0
	v_mov_b32_e32 v46, v0
	v_mov_b32_e32 v47, v0
	v_mov_b32_e32 v48, v0
	v_mov_b32_e32 v49, v0
	v_mov_b32_e32 v50, v0
	v_mov_b32_e32 v51, v0
	v_mov_b32_e32 v52, v0
	v_mov_b32_e32 v53, v0
	v_mov_b32_e32 v54, v0
	v_mov_b32_e32 v55, v0
	v_mov_b32_e32 v64, v0
	v_mov_b32_e32 v65, v0
	v_mov_b32_e32 v66, v0
	v_mov_b32_e32 v67, v0
	v_mov_b32_e32 v68, v0
	v_mov_b32_e32 v69, v0
	v_mov_b32_e32 v70, v0
	v_mov_b32_e32 v71, v0
	v_mov_b32_e32 v96, v0
	v_mov_b32_e32 v97, v0
	v_mov_b32_e32 v98, v0
	v_mov_b32_e32 v99, v0
	v_mov_b32_e32 v100, v0
	v_mov_b32_e32 v101, v0
	v_mov_b32_e32 v102, v0
	v_mov_b32_e32 v103, v0
	v_mov_b32_e32 v104, v0
	v_mov_b32_e32 v105, v0
	v_mov_b32_e32 v106, v0
	v_mov_b32_e32 v107, v0
	v_mov_b32_e32 v108, v0
	v_mov_b32_e32 v109, v0
	v_mov_b32_e32 v110, v0
	v_mov_b32_e32 v111, v0
	v_mov_b32_e32 v112, v0
	v_mov_b32_e32 v113, v0
	v_mov_b32_e32 v114, v0
	v_mov_b32_e32 v115, v0
	v_mov_b32_e32 v116, v0
	v_mov_b32_e32 v117, v0
	v_mov_b32_e32 v118, v0
	v_mov_b32_e32 v119, v0
	v_mov_b32_e32 v120, v0
	v_mov_b32_e32 v121, v0
	v_mov_b32_e32 v122, v0
	v_mov_b32_e32 v123, v0
	v_mov_b32_e32 v124, v0
	v_mov_b32_e32 v125, v0
	v_mov_b32_e32 v126, v0
	v_mov_b32_e32 v127, v0
	.p2align 6

.LBB0_376:
	s_ashr_i32 s59, s58, 31
	s_lshl_b64 s[12:13], s[58:59], 19
	v_readlane_b32 s14, v253, 29
	v_mov_b64_e32 v[0:1], 0x200
	v_readlane_b32 s15, v253, 30
	s_add_u32 s64, s14, s12
	v_cmp_lt_i64_e32 vcc, s[20:21], v[0:1]
	s_addc_u32 s65, s15, s13
	s_and_b64 s[12:13], vcc, exec
	s_cselect_b32 s20, s65, s7
	s_cselect_b32 s21, s64, s6
	s_ashr_i32 s1, s0, 31
	s_lshl_b64 s[12:13], s[0:1], 19
	s_add_u32 s66, s50, s12
	s_addc_u32 s67, s56, s13
	s_and_b64 s[12:13], vcc, exec
	s_cselect_b32 s1, s67, s9
	s_cselect_b32 s12, s66, s8
	s_add_u32 s6, s6, 0x40080
	s_addc_u32 s7, s7, 0
	s_add_u32 s13, s8, 0x100
	v_mov_b32_e32 v0, 0
	s_addc_u32 s14, s9, 0
	s_mov_b32 s15, -2
	v_mov_b32_e32 v1, v0
	v_mov_b32_e32 v2, v0
	v_mov_b32_e32 v3, v0
	v_mov_b32_e32 v4, v0
	v_mov_b32_e32 v5, v0
	v_mov_b32_e32 v6, v0
	v_mov_b32_e32 v7, v0
	v_mov_b32_e32 v8, v0
	v_mov_b32_e32 v9, v0
	v_mov_b32_e32 v10, v0
	v_mov_b32_e32 v11, v0
	v_mov_b32_e32 v12, v0
	v_mov_b32_e32 v13, v0
	v_mov_b32_e32 v14, v0
	v_mov_b32_e32 v15, v0
	v_mov_b32_e32 v16, v0
	v_mov_b32_e32 v17, v0
	v_mov_b32_e32 v18, v0
	v_mov_b32_e32 v19, v0
	v_mov_b32_e32 v20, v0
	v_mov_b32_e32 v21, v0
	v_mov_b32_e32 v22, v0
	v_mov_b32_e32 v23, v0
	v_mov_b32_e32 v24, v0
	v_mov_b32_e32 v25, v0
	v_mov_b32_e32 v26, v0
	v_mov_b32_e32 v27, v0
	v_mov_b32_e32 v28, v0
	v_mov_b32_e32 v29, v0
	v_mov_b32_e32 v30, v0
	v_mov_b32_e32 v31, v0
	v_mov_b32_e32 v64, v0
	v_mov_b32_e32 v65, v0
	v_mov_b32_e32 v66, v0
	v_mov_b32_e32 v67, v0
	v_mov_b32_e32 v68, v0
	v_mov_b32_e32 v69, v0
	v_mov_b32_e32 v70, v0
	v_mov_b32_e32 v71, v0
	v_mov_b32_e32 v72, v0
	v_mov_b32_e32 v73, v0
	v_mov_b32_e32 v74, v0
	v_mov_b32_e32 v75, v0
	v_mov_b32_e32 v76, v0
	v_mov_b32_e32 v77, v0
	v_mov_b32_e32 v78, v0
	v_mov_b32_e32 v79, v0
	v_mov_b32_e32 v80, v0
	v_mov_b32_e32 v81, v0
	v_mov_b32_e32 v82, v0
	v_mov_b32_e32 v83, v0
	v_mov_b32_e32 v84, v0
	v_mov_b32_e32 v85, v0
	v_mov_b32_e32 v86, v0
	v_mov_b32_e32 v87, v0
	v_mov_b32_e32 v88, v0
	v_mov_b32_e32 v89, v0
	v_mov_b32_e32 v90, v0
	v_mov_b32_e32 v91, v0
	v_mov_b32_e32 v92, v0
	v_mov_b32_e32 v93, v0
	v_mov_b32_e32 v94, v0
	v_mov_b32_e32 v95, v0
	v_mov_b32_e32 v32, v0
	v_mov_b32_e32 v33, v0
	v_mov_b32_e32 v34, v0
	v_mov_b32_e32 v35, v0
	v_mov_b32_e32 v36, v0
	v_mov_b32_e32 v37, v0
	v_mov_b32_e32 v38, v0
	v_mov_b32_e32 v39, v0
	v_mov_b32_e32 v40, v0
	v_mov_b32_e32 v41, v0
	v_mov_b32_e32 v42, v0
	v_mov_b32_e32 v43, v0
	v_mov_b32_e32 v44, v0
	v_mov_b32_e32 v45, v0
	v_mov_b32_e32 v46, v0
	v_mov_b32_e32 v47, v0
	v_mov_b32_e32 v48, v0
	v_mov_b32_e32 v49, v0
	v_mov_b32_e32 v50, v0
	v_mov_b32_e32 v51, v0
	v_mov_b32_e32 v52, v0
	v_mov_b32_e32 v53, v0
	v_mov_b32_e32 v54, v0
	v_mov_b32_e32 v55, v0
	v_mov_b32_e32 v56, v0
	v_mov_b32_e32 v57, v0
	v_mov_b32_e32 v58, v0
	v_mov_b32_e32 v59, v0
	v_mov_b32_e32 v60, v0
	v_mov_b32_e32 v61, v0
	v_mov_b32_e32 v62, v0
	v_mov_b32_e32 v63, v0
	v_mov_b32_e32 v96, v0
	v_mov_b32_e32 v97, v0
	v_mov_b32_e32 v98, v0
	v_mov_b32_e32 v99, v0
	v_mov_b32_e32 v100, v0
	v_mov_b32_e32 v101, v0
	v_mov_b32_e32 v102, v0
	v_mov_b32_e32 v103, v0
	v_mov_b32_e32 v112, v0
	v_mov_b32_e32 v113, v0
	v_mov_b32_e32 v114, v0
	v_mov_b32_e32 v115, v0
	v_mov_b32_e32 v116, v0
	v_mov_b32_e32 v117, v0
	v_mov_b32_e32 v118, v0
	v_mov_b32_e32 v119, v0
	v_mov_b32_e32 v120, v0
	v_mov_b32_e32 v121, v0
	v_mov_b32_e32 v122, v0
	v_mov_b32_e32 v123, v0
	v_mov_b32_e32 v124, v0
	v_mov_b32_e32 v125, v0
	v_mov_b32_e32 v126, v0
	v_mov_b32_e32 v127, v0
	v_mov_b32_e32 v128, v0
	v_mov_b32_e32 v129, v0
	v_mov_b32_e32 v130, v0
	v_mov_b32_e32 v131, v0
	v_mov_b32_e32 v132, v0
	v_mov_b32_e32 v133, v0
	v_mov_b32_e32 v134, v0
	v_mov_b32_e32 v135, v0
	.p2align 6

.LBB0_452:
	s_ashr_i32 s7, s6, 31
	s_lshl_b64 s[8:9], s[6:7], 17
	v_readlane_b32 s5, v251, 22
	s_add_u32 s66, s5, s8
	v_readlane_b32 s5, v251, 23
	s_addc_u32 s67, s5, s9
	s_and_b64 s[0:1], s[0:1], exec
	v_mov_b32_e32 v0, 0
	s_cselect_b32 s5, s67, s59
	s_cselect_b32 s7, s66, s58
	s_mov_b64 s[92:93], 0
	s_mov_b64 s[0:1], -1
	s_mov_b64 s[62:63], 0
	v_mov_b32_e32 v1, v0
	v_mov_b32_e32 v2, v0
	v_mov_b32_e32 v3, v0
	v_mov_b32_e32 v4, v0
	v_mov_b32_e32 v5, v0
	v_mov_b32_e32 v6, v0
	v_mov_b32_e32 v7, v0
	v_mov_b32_e32 v8, v0
	v_mov_b32_e32 v9, v0
	v_mov_b32_e32 v10, v0
	v_mov_b32_e32 v11, v0
	v_mov_b32_e32 v12, v0
	v_mov_b32_e32 v13, v0
	v_mov_b32_e32 v14, v0
	v_mov_b32_e32 v15, v0
	v_mov_b32_e32 v16, v0
	v_mov_b32_e32 v17, v0
	v_mov_b32_e32 v18, v0
	v_mov_b32_e32 v19, v0
	v_mov_b32_e32 v20, v0
	v_mov_b32_e32 v21, v0
	v_mov_b32_e32 v22, v0
	v_mov_b32_e32 v23, v0
	v_mov_b32_e32 v24, v0
	v_mov_b32_e32 v25, v0
	v_mov_b32_e32 v26, v0
	v_mov_b32_e32 v27, v0
	v_mov_b32_e32 v28, v0
	v_mov_b32_e32 v29, v0
	v_mov_b32_e32 v30, v0
	v_mov_b32_e32 v31, v0
	v_mov_b32_e32 v64, v0
	v_mov_b32_e32 v65, v0
	v_mov_b32_e32 v66, v0
	v_mov_b32_e32 v67, v0
	v_mov_b32_e32 v68, v0
	v_mov_b32_e32 v69, v0
	v_mov_b32_e32 v70, v0
	v_mov_b32_e32 v71, v0
	v_mov_b32_e32 v72, v0
	v_mov_b32_e32 v73, v0
	v_mov_b32_e32 v74, v0
	v_mov_b32_e32 v75, v0
	v_mov_b32_e32 v80, v0
	v_mov_b32_e32 v81, v0
	v_mov_b32_e32 v82, v0
	v_mov_b32_e32 v83, v0
	v_mov_b32_e32 v92, v0
	v_mov_b32_e32 v93, v0
	v_mov_b32_e32 v94, v0
	v_mov_b32_e32 v95, v0
	v_mov_b32_e32 v96, v0
	v_mov_b32_e32 v97, v0
	v_mov_b32_e32 v98, v0
	v_mov_b32_e32 v99, v0
	v_mov_b32_e32 v100, v0
	v_mov_b32_e32 v101, v0
	v_mov_b32_e32 v102, v0
	v_mov_b32_e32 v103, v0
	v_mov_b32_e32 v104, v0
	v_mov_b32_e32 v105, v0
	v_mov_b32_e32 v106, v0
	v_mov_b32_e32 v107, v0
	v_mov_b32_e32 v32, v0
	v_mov_b32_e32 v33, v0
	v_mov_b32_e32 v34, v0
	v_mov_b32_e32 v35, v0
	v_mov_b32_e32 v36, v0
	v_mov_b32_e32 v37, v0
	v_mov_b32_e32 v38, v0
	v_mov_b32_e32 v39, v0
	v_mov_b32_e32 v40, v0
	v_mov_b32_e32 v41, v0
	v_mov_b32_e32 v42, v0
	v_mov_b32_e32 v43, v0
	v_mov_b32_e32 v44, v0
	v_mov_b32_e32 v45, v0
	v_mov_b32_e32 v46, v0
	v_mov_b32_e32 v47, v0
	v_mov_b32_e32 v48, v0
	v_mov_b32_e32 v49, v0
	v_mov_b32_e32 v50, v0
	v_mov_b32_e32 v51, v0
	v_mov_b32_e32 v52, v0
	v_mov_b32_e32 v53, v0
	v_mov_b32_e32 v54, v0
	v_mov_b32_e32 v55, v0
	v_mov_b32_e32 v56, v0
	v_mov_b32_e32 v57, v0
	v_mov_b32_e32 v58, v0
	v_mov_b32_e32 v59, v0
	v_mov_b32_e32 v60, v0
	v_mov_b32_e32 v61, v0
	v_mov_b32_e32 v62, v0
	v_mov_b32_e32 v63, v0
	v_mov_b32_e32 v108, v0
	v_mov_b32_e32 v109, v0
	v_mov_b32_e32 v110, v0
	v_mov_b32_e32 v111, v0
	v_mov_b32_e32 v112, v0
	v_mov_b32_e32 v113, v0
	v_mov_b32_e32 v114, v0
	v_mov_b32_e32 v115, v0
	v_mov_b32_e32 v116, v0
	v_mov_b32_e32 v117, v0
	v_mov_b32_e32 v118, v0
	v_mov_b32_e32 v119, v0
	v_mov_b32_e32 v120, v0
	v_mov_b32_e32 v121, v0
	v_mov_b32_e32 v122, v0
	v_mov_b32_e32 v123, v0
	v_mov_b32_e32 v124, v0
	v_mov_b32_e32 v125, v0
	v_mov_b32_e32 v126, v0
	v_mov_b32_e32 v127, v0
	v_mov_b32_e32 v128, v0
	v_mov_b32_e32 v129, v0
	v_mov_b32_e32 v130, v0
	v_mov_b32_e32 v131, v0
	v_mov_b32_e32 v132, v0
	v_mov_b32_e32 v133, v0
	v_mov_b32_e32 v134, v0
	v_mov_b32_e32 v135, v0
	v_mov_b32_e32 v136, v0
	v_mov_b32_e32 v137, v0
	v_mov_b32_e32 v138, v0
	v_mov_b32_e32 v139, v0
	.p2align 6

.LBB0_1039:
	s_ashr_i32 s7, s6, 31
	s_lshl_b64 s[12:13], s[6:7], 19
	v_readlane_b32 s7, v253, 49
	s_add_u32 s58, s7, s12
	v_readlane_b32 s7, v253, 50
	s_addc_u32 s59, s7, s13
	s_and_b64 s[0:1], s[0:1], exec
	s_cselect_b32 s7, s59, s5
	s_cselect_b32 s12, s58, s4
	s_add_u32 s0, s8, 0x40080
	s_addc_u32 s1, s9, 0
	s_add_u32 s13, s4, 0x100
	v_mov_b32_e32 v0, 0
	s_addc_u32 s14, s5, 0
	s_mov_b32 s15, -2
	v_mov_b32_e32 v1, v0
	v_mov_b32_e32 v2, v0
	v_mov_b32_e32 v3, v0
	v_mov_b32_e32 v4, v0
	v_mov_b32_e32 v5, v0
	v_mov_b32_e32 v6, v0
	v_mov_b32_e32 v7, v0
	v_mov_b32_e32 v8, v0
	v_mov_b32_e32 v9, v0
	v_mov_b32_e32 v10, v0
	v_mov_b32_e32 v11, v0
	v_mov_b32_e32 v12, v0
	v_mov_b32_e32 v13, v0
	v_mov_b32_e32 v14, v0
	v_mov_b32_e32 v15, v0
	v_mov_b32_e32 v16, v0
	v_mov_b32_e32 v17, v0
	v_mov_b32_e32 v18, v0
	v_mov_b32_e32 v19, v0
	v_mov_b32_e32 v20, v0
	v_mov_b32_e32 v21, v0
	v_mov_b32_e32 v22, v0
	v_mov_b32_e32 v23, v0
	v_mov_b32_e32 v24, v0
	v_mov_b32_e32 v25, v0
	v_mov_b32_e32 v26, v0
	v_mov_b32_e32 v27, v0
	v_mov_b32_e32 v28, v0
	v_mov_b32_e32 v29, v0
	v_mov_b32_e32 v30, v0
	v_mov_b32_e32 v31, v0
	v_mov_b32_e32 v60, v0
	v_mov_b32_e32 v61, v0
	v_mov_b32_e32 v62, v0
	v_mov_b32_e32 v63, v0
	v_mov_b32_e32 v68, v0
	v_mov_b32_e32 v69, v0
	v_mov_b32_e32 v70, v0
	v_mov_b32_e32 v71, v0
	v_mov_b32_e32 v72, v0
	v_mov_b32_e32 v73, v0
	v_mov_b32_e32 v74, v0
	v_mov_b32_e32 v75, v0
	v_mov_b32_e32 v76, v0
	v_mov_b32_e32 v77, v0
	v_mov_b32_e32 v78, v0
	v_mov_b32_e32 v79, v0
	v_mov_b32_e32 v80, v0
	v_mov_b32_e32 v81, v0
	v_mov_b32_e32 v82, v0
	v_mov_b32_e32 v83, v0
	v_mov_b32_e32 v84, v0
	v_mov_b32_e32 v85, v0
	v_mov_b32_e32 v86, v0
	v_mov_b32_e32 v87, v0
	v_mov_b32_e32 v88, v0
	v_mov_b32_e32 v89, v0
	v_mov_b32_e32 v90, v0
	v_mov_b32_e32 v91, v0
	v_mov_b32_e32 v92, v0
	v_mov_b32_e32 v93, v0
	v_mov_b32_e32 v94, v0
	v_mov_b32_e32 v95, v0
	v_mov_b32_e32 v32, v0
	v_mov_b32_e32 v33, v0
	v_mov_b32_e32 v34, v0
	v_mov_b32_e32 v35, v0
	v_mov_b32_e32 v36, v0
	v_mov_b32_e32 v37, v0
	v_mov_b32_e32 v38, v0
	v_mov_b32_e32 v39, v0
	v_mov_b32_e32 v40, v0
	v_mov_b32_e32 v41, v0
	v_mov_b32_e32 v42, v0
	v_mov_b32_e32 v43, v0
	v_mov_b32_e32 v44, v0
	v_mov_b32_e32 v45, v0
	v_mov_b32_e32 v46, v0
	v_mov_b32_e32 v47, v0
	v_mov_b32_e32 v48, v0
	v_mov_b32_e32 v49, v0
	v_mov_b32_e32 v50, v0
	v_mov_b32_e32 v51, v0
	v_mov_b32_e32 v52, v0
	v_mov_b32_e32 v53, v0
	v_mov_b32_e32 v54, v0
	v_mov_b32_e32 v55, v0
	v_mov_b32_e32 v56, v0
	v_mov_b32_e32 v57, v0
	v_mov_b32_e32 v58, v0
	v_mov_b32_e32 v59, v0
	v_mov_b32_e32 v64, v0
	v_mov_b32_e32 v65, v0
	v_mov_b32_e32 v66, v0
	v_mov_b32_e32 v67, v0
	v_mov_b32_e32 v96, v0
	v_mov_b32_e32 v97, v0
	v_mov_b32_e32 v98, v0
	v_mov_b32_e32 v99, v0
	v_mov_b32_e32 v100, v0
	v_mov_b32_e32 v101, v0
	v_mov_b32_e32 v102, v0
	v_mov_b32_e32 v103, v0
	v_mov_b32_e32 v104, v0
	v_mov_b32_e32 v105, v0
	v_mov_b32_e32 v106, v0
	v_mov_b32_e32 v107, v0
	v_mov_b32_e32 v108, v0
	v_mov_b32_e32 v109, v0
	v_mov_b32_e32 v110, v0
	v_mov_b32_e32 v111, v0
	v_mov_b32_e32 v112, v0
	v_mov_b32_e32 v113, v0
	v_mov_b32_e32 v114, v0
	v_mov_b32_e32 v115, v0
	v_mov_b32_e32 v116, v0
	v_mov_b32_e32 v117, v0
	v_mov_b32_e32 v118, v0
	v_mov_b32_e32 v119, v0
	v_mov_b32_e32 v120, v0
	v_mov_b32_e32 v121, v0
	v_mov_b32_e32 v122, v0
	v_mov_b32_e32 v123, v0
	v_mov_b32_e32 v124, v0
	v_mov_b32_e32 v125, v0
	v_mov_b32_e32 v126, v0
	v_mov_b32_e32 v127, v0
	.p2align 6
